# attention: first unit's Q loads drained before the loop so the QK block waits on LDS only (its vmcnt waits covered most of the next unit's prefetch); plus prepass, final rmsnorm, GEMM store and K-loop
# baseline (speedup 1.0000x reference)
; #define LAS __attribute__((address_space(3)))
; #define MFMA16(a, b, c) __builtin_amdgcn_mfma_f32_16x16x32_bf16((a), (b), (c), 0, 0, 0)
; #define ATT_LOADK(buf, T) do { _Pragma("unroll") for (int ks_ = 0; ks_ < 4; ++ks_) kf[buf][ks_] = *(const LAS bf16x8*)(kb + ((16 * (wave + (T))) ^ u.sx) * KV_STRIDE + 64 * ks_); } while (0)
; __device__ __forceinline__ void attn_load(AttnPre& P, const bf16* Z, const AttnUid& u, int tid, int wave, int lane) {
;     ...
;     const int fr = lane & 15, fq = lane >> 4;
;     const int qsub = u.n * 128 + 16 * wave + fr;
;     const bf16* qp = Zb + (size_t)(qsub * u.d + u.r) * INW + 2048 + h * HD + 8 * fq;
; #pragma unroll
;     for (int ks = 0; ks < 4; ++ks) P.q[ks] = *(const bf16x8*)(qp + 32 * ks);
; __device__ __forceinline__ void attn_compute(LAS unsigned char* lds, const bf16x8 (&qf)[4], const AttnUid& u, bf16* ON, float* LSE, int wave, int lane) {
;     const int fr = lane & 15, fq = lane >> 4;
;     const int qi = 16 * wave + fr;
;     const int qsub = u.n * 128 + qi;
;     f32x4 S[10];
;     const LAS unsigned char* kb = lds + fr * KV_STRIDE + 16 * fq;
;     bf16x8 kf[3][4];
;     ...
;     ATT_LOADK(0, 0); ATT_LOADK(1, 1);
; #pragma unroll
;     for (int T = 0; T < 9; ++T) {
;         if (T + 2 < 9) ATT_LOADK((T + 2) % 3, T + 2);
;         __builtin_amdgcn_sched_barrier(0);
;         S[T] = (f32x4){0.f, 0.f, 0.f, 0.f};
; #pragma unroll
;         for (int ks = 0; ks < 4; ++ks) S[T] = MFMA16(kf[T % 3][ks], qf[ks], S[T]);
;         __builtin_amdgcn_sched_barrier(0);
;     }
;     ...
;     S[9] = (f32x4){0.f, 0.f, 0.f, 0.f};
;     const float NEG = -1.0e30f;
; #pragma unroll
;     for (int i = 0; i < 4; ++i) { if (4 * fq + i < fr) S[0][i] = NEG; if (4 * fq + i > fr) S[8][i] = NEG; }
;     if (u.n == 0) {
; #pragma unroll
;         for (int T = 0; T < 9; ++T)
; #pragma unroll
;             for (int i = 0; i < 4; ++i) if (16 * wave + 16 * T + 4 * fq + i < 128) S[T][i] = NEG;
.LBB0_219:
	s_or_b64 exec, exec, s[2:3]
	s_lshl_b32 s97, s4, 4
	v_and_b32_e32 v1, 15, v70
	s_add_i32 s2, s58, s97
	v_or_b32_e32 v2, s2, v1
	v_lshlrev_b32_e32 v2, s53, v2
	v_add_u32_e32 v68, s55, v2
	v_mov_b64_e32 v[2:3], s[0:1]
	v_mad_i64_i32 v[2:3], s[0:1], v68, s59, v[2:3]
	v_ashrrev_i32_e32 v68, 1, v70
	v_and_b32_e32 v130, -8, v68
	v_lshl_add_u64 v[2:3], v[2:3], 0, s[56:57]
	v_ashrrev_i32_e32 v131, 31, v130
	v_lshl_add_u64 v[2:3], v[130:131], 1, v[2:3]
	s_mov_b64 s[0:1], 0x1000
	v_lshl_add_u64 v[68:69], v[2:3], 0, s[0:1]
	v_add_co_u32_e32 v2, vcc, s60, v2
	s_add_i32 s0, 0, 0x12000
	s_nop 0
	v_addc_co_u32_e32 v3, vcc, 0, v3, vcc
	global_load_dwordx4 v[84:87], v[2:3], off
	global_load_dwordx4 v[92:95], v[68:69], off offset:64
	global_load_dwordx4 v[88:91], v[68:69], off offset:128
	global_load_dwordx4 v[96:99], v[68:69], off offset:192
	v_lshlrev_b32_e32 v2, 4, v70
	v_and_b32_e32 v2, 0xf0, v2
	v_add_u32_e32 v152, 0, v2
	v_add_u32_e32 v153, s0, v2
	v_mul_u32_u24_e32 v2, 0x120, v1
	v_and_b32_e32 v3, -16, v70
	v_add3_u32 v167, 0, v2, v3
	v_ashrrev_i32_e32 v2, 2, v70
	v_and_b32_e32 v3, -4, v2
	v_or_b32_e32 v68, 1, v3
	v_cmp_lt_i32_e64 s[8:9], v68, v1
	v_or_b32_e32 v68, 2, v3
	v_cmp_lt_i32_e64 s[10:11], v68, v1
	v_cmp_gt_i32_e64 s[12:13], v68, v1
	v_or_b32_e32 v68, 3, v2
	v_or_b32_e32 v166, s97, v1
	s_movk_i32 s24, 0x80
	v_cmp_lt_i32_e64 s[4:5], v3, v1
	v_cmp_gt_i32_e64 s[6:7], v3, v1
	v_cmp_lt_i32_e64 s[14:15], v68, v1
	v_cmp_gt_i32_e64 s[16:17], v68, v1
	v_add_u32_e32 v1, s97, v3
	v_cmp_gt_i32_e64 s[18:19], s24, v1
	v_or_b32_e32 v68, 1, v1
	s_add_i32 s2, s97, 16
	v_writelane_b32 v251, s18, 51
	s_add_i32 s3, s97, 32
	s_add_i32 s20, s97, 48
	v_writelane_b32 v251, s19, 52
	v_cmp_gt_i32_e64 s[18:19], s24, v68
	v_or_b32_e32 v68, 2, v1
	v_or_b32_e32 v1, 3, v1
	v_writelane_b32 v251, s18, 53
	s_add_i32 s21, s97, 64
	s_add_i32 s96, s97, 0x50
	v_writelane_b32 v251, s19, 54
	v_cmp_gt_i32_e64 s[18:19], s24, v68
	s_mov_b32 s29, s55
	s_mov_b32 s55, s57
	v_writelane_b32 v251, s18, 55
	s_add_i32 s22, s97, 0x60
	s_add_i32 s23, s97, 0x70
	v_writelane_b32 v251, s19, 56
	v_cmp_gt_i32_e64 s[18:19], s24, v1
	v_add_u32_e32 v1, s2, v3
	v_or_b32_e32 v68, 1, v1
	v_writelane_b32 v251, s18, 57
	s_add_i32 s25, s97, 0x80
	s_mov_b32 s39, s53
	v_writelane_b32 v251, s19, 58
	v_cmp_gt_i32_e64 s[18:19], s24, v1
	s_movk_i32 s53, 0x120
	v_and_b32_e32 v132, -8, v2
	v_writelane_b32 v251, s18, 59
	v_and_b32_e32 v2, 16, v70
	s_movk_i32 s52, 0x2800
	v_writelane_b32 v251, s19, 60
	v_cmp_gt_i32_e64 s[18:19], s24, v68
	v_or_b32_e32 v68, 2, v1
	v_or_b32_e32 v1, 3, v1
	v_writelane_b32 v251, s18, 61
	s_mov_b32 s33, 1
	s_mov_b32 s35, 0
	v_writelane_b32 v251, s19, 62
	v_cmp_gt_i32_e64 s[18:19], s24, v68
	v_ashrrev_i32_e32 v133, 31, v132
	v_cmp_gt_u32_e64 s[92:93], 16, v70
	v_writelane_b32 v251, s18, 63
	s_mov_b32 s26, 8
	v_lshlrev_b32_e32 v134, 1, v2
	v_writelane_b32 v250, s19, 0
	v_cmp_gt_i32_e64 s[18:19], s24, v1
	v_add_u32_e32 v1, s3, v3
	v_or_b32_e32 v68, 1, v1
	v_writelane_b32 v250, s18, 1
	s_mov_b32 s30, 0
	v_readlane_b32 s41, v251, 2
	v_writelane_b32 v250, s19, 2
	v_cmp_gt_i32_e64 s[18:19], s24, v1
	v_readlane_b32 s37, v252, 61
	v_readlane_b32 s34, v252, 45
	v_writelane_b32 v250, s18, 3
	s_nop 1
	v_writelane_b32 v250, s19, 4
	v_cmp_gt_i32_e64 s[18:19], s24, v68
	v_or_b32_e32 v68, 2, v1
	v_or_b32_e32 v1, 3, v1
	v_writelane_b32 v250, s18, 5
	s_nop 1
	v_writelane_b32 v250, s19, 6
	v_cmp_gt_i32_e64 s[18:19], s24, v68
	s_nop 1
	v_writelane_b32 v250, s18, 7
	s_nop 1
	v_writelane_b32 v250, s19, 8
	v_cmp_gt_i32_e64 s[18:19], s24, v1
	v_add_u32_e32 v1, s20, v3
	v_or_b32_e32 v68, 1, v1
	v_writelane_b32 v250, s18, 9
	s_nop 1
	v_writelane_b32 v250, s19, 10
	v_cmp_gt_i32_e64 s[18:19], s24, v1
	s_nop 1
	v_writelane_b32 v250, s18, 11
	s_nop 1
	v_writelane_b32 v250, s19, 12
	v_cmp_gt_i32_e64 s[18:19], s24, v68
	v_or_b32_e32 v68, 2, v1
	v_or_b32_e32 v1, 3, v1
	v_writelane_b32 v250, s18, 13
	s_nop 1
	v_writelane_b32 v250, s19, 14
	v_cmp_gt_i32_e64 s[18:19], s24, v68
	s_nop 1
	v_writelane_b32 v250, s18, 15
	s_nop 1
	v_writelane_b32 v250, s19, 16
	v_cmp_gt_i32_e64 s[18:19], s24, v1
	v_add_u32_e32 v1, s21, v3
	v_or_b32_e32 v68, 1, v1
	v_writelane_b32 v250, s18, 17
	s_nop 1
	v_writelane_b32 v250, s19, 18
	v_cmp_gt_i32_e64 s[18:19], s24, v1
	s_nop 1
	v_writelane_b32 v250, s18, 19
	s_nop 1
	v_writelane_b32 v250, s19, 20
	v_cmp_gt_i32_e64 s[18:19], s24, v68
	v_or_b32_e32 v68, 2, v1
	v_or_b32_e32 v1, 3, v1
	v_cmp_gt_i32_e64 s[58:59], s24, v1
	v_add_u32_e32 v1, s96, v3
	v_cmp_gt_i32_e64 s[56:57], s24, v68
	v_or_b32_e32 v68, 1, v1
	v_cmp_gt_i32_e64 s[60:61], s24, v1
	v_cmp_gt_i32_e64 s[62:63], s24, v68
	v_or_b32_e32 v68, 2, v1
	v_or_b32_e32 v1, 3, v1
	v_cmp_gt_i32_e64 s[66:67], s24, v1
	v_add_u32_e32 v1, s22, v3
	v_cmp_gt_i32_e64 s[64:65], s24, v68
	v_or_b32_e32 v68, 1, v1
	v_cmp_gt_i32_e64 s[68:69], s24, v1
	v_cmp_gt_i32_e64 s[70:71], s24, v68
	v_or_b32_e32 v68, 2, v1
	v_or_b32_e32 v1, 3, v1
	v_cmp_gt_i32_e64 s[74:75], s24, v1
	v_add_u32_e32 v1, s23, v3
	v_cmp_gt_i32_e64 s[72:73], s24, v68
	v_or_b32_e32 v68, 1, v1
	v_cmp_gt_i32_e64 s[76:77], s24, v1
	v_cmp_gt_i32_e64 s[78:79], s24, v68
	v_or_b32_e32 v68, 2, v1
	v_or_b32_e32 v1, 3, v1
	v_cmp_gt_i32_e64 s[82:83], s24, v1
	v_add_u32_e32 v1, s25, v3
	v_cmp_gt_i32_e64 s[80:81], s24, v68
	v_or_b32_e32 v68, 1, v1
	v_cmp_gt_i32_e64 s[84:85], s24, v1
	v_cmp_gt_i32_e64 s[86:87], s24, v68
	v_or_b32_e32 v68, 2, v1
	v_or_b32_e32 v1, 3, v1
	v_cmp_gt_i32_e64 s[90:91], s24, v1
	v_bfe_u32 v1, v70, 2, 2
	v_or_b32_e32 v1, v3, v1
	v_mul_lo_u32 v1, v1, s53
	v_and_b32_e32 v3, 24, v71
	v_writelane_b32 v250, s18, 21
	v_cmp_gt_i32_e64 s[88:89], s24, v68
	v_add3_u32 v168, s0, v1, v3
	v_writelane_b32 v250, s19, 22
	s_waitcnt vmcnt(0)
	s_branch .LBB0_221

; #define LAS __attribute__((address_space(3)))
; #define MFMA16(a, b, c) __builtin_amdgcn_mfma_f32_16x16x32_bf16((a), (b), (c), 0, 0, 0)
; #define ATT_LOADK(buf, T) do { _Pragma("unroll") for (int ks_ = 0; ks_ < 4; ++ks_) kf[buf][ks_] = *(const LAS bf16x8*)(kb + ((16 * (wave + (T))) ^ u.sx) * KV_STRIDE + 64 * ks_); } while (0)
; __device__ __forceinline__ void attn_compute(LAS unsigned char* lds, const bf16x8 (&qf)[4], const AttnUid& u, bf16* ON, float* LSE, int wave, int lane) {
;     ...
;     const int qi = 16 * wave + fr;
;     const int qsub = u.n * 128 + qi;
;     f32x4 S[10];
;     const LAS unsigned char* kb = lds + fr * KV_STRIDE + 16 * fq;
;     bf16x8 kf[3][4];
;     ...
;     ATT_LOADK(0, 0); ATT_LOADK(1, 1);
; #pragma unroll
;     for (int T = 0; T < 9; ++T) {
;         if (T + 2 < 9) ATT_LOADK((T + 2) % 3, T + 2);
;         __builtin_amdgcn_sched_barrier(0);
;         S[T] = (f32x4){0.f, 0.f, 0.f, 0.f};
; #pragma unroll
;         for (int ks = 0; ks < 4; ++ks) S[T] = MFMA16(kf[T % 3][ks], qf[ks], S[T]);
;         __builtin_amdgcn_sched_barrier(0);
;     }
;     ...
;     S[9] = (f32x4){0.f, 0.f, 0.f, 0.f};
;     const float NEG = -1.0e30f;
; #pragma unroll
;     for (int i = 0; i < 4; ++i) { if (4 * fq + i < fr) S[0][i] = NEG; if (4 * fq + i > fr) S[8][i] = NEG; }
.LBB0_258:
	v_readlane_b32 s44, v252, 13
	s_xor_b32 s42, s35, s97
	v_readlane_b32 s46, v252, 15
	v_readlane_b32 s47, v252, 16
	s_mulk_i32 s42, 0x120
	s_xor_b32 s44, s35, s2
	s_mov_b64 s[0:1], s[46:47]
	s_mov_b64 s[94:95], s[46:47]
	v_add_u32_e32 v1, s42, v167
	s_mulk_i32 s44, 0x120
	s_xor_b32 s43, s35, s3
	ds_read_b128 v[100:103], v1
	ds_read_b128 v[104:107], v1 offset:64
	ds_read_b128 v[108:111], v1 offset:128
	ds_read_b128 v[112:115], v1 offset:192
	v_add_u32_e32 v1, s44, v167
	s_mulk_i32 s43, 0x120
	ds_read_b128 v[116:119], v1
	ds_read_b128 v[120:123], v1 offset:64
	ds_read_b128 v[124:127], v1 offset:128
	ds_read_b128 v[170:173], v1 offset:192
	v_add_u32_e32 v1, s43, v167
	ds_read_b128 v[174:177], v1
	ds_read_b128 v[178:181], v1 offset:64
	ds_read_b128 v[182:185], v1 offset:128
	ds_read_b128 v[186:189], v1 offset:192
	v_readlane_b32 s45, v252, 14
	s_waitcnt lgkmcnt(11)
	v_mfma_f32_16x16x32_bf16 v[100:103], v[100:103], v[84:87], 0
	s_waitcnt lgkmcnt(10)
	v_mfma_f32_16x16x32_bf16 v[100:103], v[104:107], v[92:95], v[100:103]
	s_waitcnt lgkmcnt(9)
	v_mfma_f32_16x16x32_bf16 v[100:103], v[108:111], v[88:91], v[100:103]
	s_waitcnt lgkmcnt(8)
	v_mfma_f32_16x16x32_bf16 v[202:205], v[112:115], v[96:99], v[100:103]
	s_xor_b32 s45, s35, s20
	s_mulk_i32 s45, 0x120
	v_add_u32_e32 v1, s45, v167
	s_nop 2
	ds_read_b128 v[100:103], v1
	ds_read_b128 v[104:107], v1 offset:64
	ds_read_b128 v[108:111], v1 offset:128
	ds_read_b128 v[112:115], v1 offset:192
	s_waitcnt lgkmcnt(11)
	v_mfma_f32_16x16x32_bf16 v[116:119], v[116:119], v[84:87], 0
	s_waitcnt lgkmcnt(10)
	v_mfma_f32_16x16x32_bf16 v[116:119], v[120:123], v[92:95], v[116:119]
	s_waitcnt lgkmcnt(9)
	v_mfma_f32_16x16x32_bf16 v[116:119], v[124:127], v[88:91], v[116:119]
	s_waitcnt lgkmcnt(8)
	v_mfma_f32_16x16x32_bf16 v[124:127], v[170:173], v[96:99], v[116:119]
	s_xor_b32 s46, s35, s21
	s_mulk_i32 s46, 0x120
	v_add_u32_e32 v1, s46, v167
	ds_read_b128 v[170:173], v1
	ds_read_b128 v[206:209], v1 offset:64
	ds_read_b128 v[210:213], v1 offset:128
	ds_read_b128 v[214:217], v1 offset:192
	s_waitcnt lgkmcnt(11)
	v_mfma_f32_16x16x32_bf16 v[116:119], v[174:177], v[84:87], 0
	s_waitcnt lgkmcnt(10)
	v_mfma_f32_16x16x32_bf16 v[116:119], v[178:181], v[92:95], v[116:119]
	s_waitcnt lgkmcnt(9)
	v_mfma_f32_16x16x32_bf16 v[116:119], v[182:185], v[88:91], v[116:119]
	s_waitcnt lgkmcnt(8)
	v_mfma_f32_16x16x32_bf16 v[120:123], v[186:189], v[96:99], v[116:119]
	s_xor_b32 s47, s35, s96
	s_mulk_i32 s47, 0x120
	v_add_u32_e32 v1, s47, v167
	ds_read_b128 v[174:177], v1
	ds_read_b128 v[178:181], v1 offset:64
	ds_read_b128 v[182:185], v1 offset:128
	ds_read_b128 v[186:189], v1 offset:192
	s_waitcnt lgkmcnt(11)
	v_mfma_f32_16x16x32_bf16 v[100:103], v[100:103], v[84:87], 0
	s_waitcnt lgkmcnt(10)
	v_mfma_f32_16x16x32_bf16 v[100:103], v[104:107], v[92:95], v[100:103]
	s_waitcnt lgkmcnt(9)
	v_mfma_f32_16x16x32_bf16 v[100:103], v[108:111], v[88:91], v[100:103]
	s_waitcnt lgkmcnt(8)
	v_mfma_f32_16x16x32_bf16 v[116:119], v[112:115], v[96:99], v[100:103]
	s_xor_b32 s48, s35, s22
	s_mulk_i32 s48, 0x120
	v_add_u32_e32 v1, s48, v167
	s_nop 2
	ds_read_b128 v[100:103], v1
	ds_read_b128 v[104:107], v1 offset:64
	ds_read_b128 v[218:221], v1 offset:128
	ds_read_b128 v[222:225], v1 offset:192
	s_waitcnt lgkmcnt(11)
	v_mfma_f32_16x16x32_bf16 v[108:111], v[170:173], v[84:87], 0
	s_waitcnt lgkmcnt(10)
	v_mfma_f32_16x16x32_bf16 v[108:111], v[206:209], v[92:95], v[108:111]
	s_waitcnt lgkmcnt(9)
	v_mfma_f32_16x16x32_bf16 v[108:111], v[210:213], v[88:91], v[108:111]
	s_waitcnt lgkmcnt(8)
	v_mfma_f32_16x16x32_bf16 v[112:115], v[214:217], v[96:99], v[108:111]
	s_xor_b32 s49, s35, s23
	s_mulk_i32 s49, 0x120
	v_add_u32_e32 v1, s49, v167
	ds_read_b128 v[170:173], v1
	ds_read_b128 v[206:209], v1 offset:64
	ds_read_b128 v[210:213], v1 offset:128
	ds_read_b128 v[214:217], v1 offset:192
	s_waitcnt lgkmcnt(11)
	v_mfma_f32_16x16x32_bf16 v[108:111], v[174:177], v[84:87], 0
	s_waitcnt lgkmcnt(10)
	v_mfma_f32_16x16x32_bf16 v[108:111], v[178:181], v[92:95], v[108:111]
	s_waitcnt lgkmcnt(9)
	v_mfma_f32_16x16x32_bf16 v[108:111], v[182:185], v[88:91], v[108:111]
	s_waitcnt lgkmcnt(8)
	v_mfma_f32_16x16x32_bf16 v[108:111], v[186:189], v[96:99], v[108:111]
	s_xor_b32 s35, s35, s25
	s_mulk_i32 s35, 0x120
	v_add_u32_e32 v1, s35, v167
	ds_read_b128 v[174:177], v1
	ds_read_b128 v[178:181], v1 offset:64
	ds_read_b128 v[182:185], v1 offset:128
	ds_read_b128 v[186:189], v1 offset:192
	s_waitcnt lgkmcnt(11)
	v_mfma_f32_16x16x32_bf16 v[100:103], v[100:103], v[84:87], 0
	s_waitcnt lgkmcnt(10)
	v_mfma_f32_16x16x32_bf16 v[100:103], v[104:107], v[92:95], v[100:103]
	s_waitcnt lgkmcnt(9)
	v_mfma_f32_16x16x32_bf16 v[100:103], v[218:221], v[88:91], v[100:103]
	s_waitcnt lgkmcnt(8)
	v_mfma_f32_16x16x32_bf16 v[104:107], v[222:225], v[96:99], v[100:103]
	s_waitcnt lgkmcnt(7)
	v_mfma_f32_16x16x32_bf16 v[100:103], v[170:173], v[84:87], 0
	s_waitcnt lgkmcnt(6)
	v_mfma_f32_16x16x32_bf16 v[100:103], v[206:209], v[92:95], v[100:103]
	s_waitcnt lgkmcnt(5)
	v_mfma_f32_16x16x32_bf16 v[100:103], v[210:213], v[88:91], v[100:103]
	s_waitcnt lgkmcnt(4)
	v_mfma_f32_16x16x32_bf16 v[100:103], v[214:217], v[96:99], v[100:103]
	s_waitcnt lgkmcnt(3)
	v_mfma_f32_16x16x32_bf16 v[84:87], v[174:177], v[84:87], 0
	s_waitcnt lgkmcnt(2)
	v_mfma_f32_16x16x32_bf16 v[84:87], v[178:181], v[92:95], v[84:87]
	s_waitcnt lgkmcnt(1)
	v_mfma_f32_16x16x32_bf16 v[84:87], v[182:185], v[88:91], v[84:87]
	s_waitcnt lgkmcnt(0)
	v_mfma_f32_16x16x32_bf16 v[90:93], v[186:189], v[96:99], v[84:87]
	s_mov_b32 s19, 0xf149f2ca
	v_mov_b32_e32 v2, s19
	s_nop 5
	v_cndmask_b32_e64 v1, v90, v2, s[6:7]
	v_cndmask_b32_e64 v88, v202, v2, s[4:5]
	v_cndmask_b32_e64 v87, v203, v200, s[8:9]
	v_cndmask_b32_e64 v84, v1, v90, s[4:5]
	v_cndmask_b32_e64 v1, v200, v91, s[4:5]
	v_cndmask_b32_e64 v86, v204, v200, s[10:11]
	v_cndmask_b32_e64 v2, v92, v200, s[12:13]
	v_cndmask_b32_e64 v85, v205, v200, s[14:15]
	s_cmp_lg_u32 s41, 0
	v_cndmask_b32_e64 v3, v93, v200, s[16:17]
	s_cbranch_scc1 .LBB0_260
; __device__ __forceinline__ void attn_compute(LAS unsigned char* lds, const bf16x8 (&qf)[4], const AttnUid& u, bf16* ON, float* LSE, int wave, int lane) {
;     ...
;     if (u.n == 0) {
; #pragma unroll
;         for (int T = 0; T < 9; ++T)
; #pragma unroll
;             for (int i = 0; i < 4; ++i) if (16 * wave + 16 * T + 4 * fq + i < 128) S[T][i] = NEG;
;     }
	v_readlane_b32 s50, v251, 51
	v_mov_b32_e32 v90, s19
	v_readlane_b32 s51, v251, 52
	v_cndmask_b32_e64 v114, v114, v200, s[56:57]
	v_cndmask_b32_e64 v115, v115, v200, s[58:59]
	v_cndmask_b32_e64 v88, v88, v90, s[50:51]
	v_readlane_b32 s50, v251, 53
	v_readlane_b32 s51, v251, 54
	v_cndmask_b32_e64 v108, v108, v90, s[60:61]
	v_cndmask_b32_e64 v109, v109, v200, s[62:63]
	v_cndmask_b32_e64 v87, v87, v200, s[50:51]
	v_readlane_b32 s50, v251, 55
	v_readlane_b32 s51, v251, 56
	v_cndmask_b32_e64 v110, v110, v200, s[64:65]
	v_cndmask_b32_e64 v111, v111, v200, s[66:67]
	v_cndmask_b32_e64 v86, v86, v200, s[50:51]
	v_readlane_b32 s50, v251, 57
	v_readlane_b32 s51, v251, 58
	v_cndmask_b32_e64 v104, v104, v90, s[68:69]
	v_cndmask_b32_e64 v105, v105, v200, s[70:71]
	v_cndmask_b32_e64 v85, v85, v200, s[50:51]
	v_readlane_b32 s50, v251, 59
	v_readlane_b32 s51, v251, 60
	v_cndmask_b32_e64 v106, v106, v200, s[72:73]
	v_cndmask_b32_e64 v107, v107, v200, s[74:75]
	v_cndmask_b32_e64 v124, v124, v90, s[50:51]
	v_readlane_b32 s50, v251, 61
	v_readlane_b32 s51, v251, 62
	v_cndmask_b32_e64 v100, v100, v90, s[76:77]
	v_cndmask_b32_e64 v101, v101, v200, s[78:79]
	v_cndmask_b32_e64 v125, v125, v200, s[50:51]
	v_readlane_b32 s50, v251, 63
	v_readlane_b32 s51, v250, 0
	v_cndmask_b32_e64 v102, v102, v200, s[80:81]
	v_cndmask_b32_e64 v103, v103, v200, s[82:83]
	v_cndmask_b32_e64 v126, v126, v200, s[50:51]
	v_readlane_b32 s50, v250, 1
	v_readlane_b32 s51, v250, 2
	v_cndmask_b32_e64 v84, v84, v90, s[84:85]
	v_cndmask_b32_e64 v1, v1, v200, s[86:87]
	v_cndmask_b32_e64 v127, v127, v200, s[50:51]
	v_readlane_b32 s50, v250, 3
	v_readlane_b32 s51, v250, 4
	v_cndmask_b32_e64 v2, v2, v200, s[88:89]
	v_cndmask_b32_e64 v3, v3, v200, s[90:91]
	v_cndmask_b32_e64 v120, v120, v90, s[50:51]
	v_readlane_b32 s50, v250, 5
	v_readlane_b32 s51, v250, 6
	s_nop 1
	v_cndmask_b32_e64 v121, v121, v200, s[50:51]
	v_readlane_b32 s50, v250, 7
	v_readlane_b32 s51, v250, 8
	s_nop 1
	v_cndmask_b32_e64 v122, v122, v200, s[50:51]
	v_readlane_b32 s50, v250, 9
	v_readlane_b32 s51, v250, 10
	s_nop 1
	v_cndmask_b32_e64 v123, v123, v200, s[50:51]
	v_readlane_b32 s50, v250, 11
	v_readlane_b32 s51, v250, 12
	s_nop 1
	v_cndmask_b32_e64 v116, v116, v90, s[50:51]
	v_readlane_b32 s50, v250, 13
	v_readlane_b32 s51, v250, 14
	s_nop 1
	v_cndmask_b32_e64 v117, v117, v200, s[50:51]
	v_readlane_b32 s50, v250, 15
	v_readlane_b32 s51, v250, 16
	s_nop 1
	v_cndmask_b32_e64 v118, v118, v200, s[50:51]
	v_readlane_b32 s50, v250, 17
	v_readlane_b32 s51, v250, 18
	s_nop 1
	v_cndmask_b32_e64 v119, v119, v200, s[50:51]
	v_readlane_b32 s50, v250, 19
	v_readlane_b32 s51, v250, 20
	s_nop 1
	v_cndmask_b32_e64 v112, v112, v90, s[50:51]
	v_readlane_b32 s50, v250, 21
	v_readlane_b32 s51, v250, 22
	s_nop 1
	v_cndmask_b32_e64 v113, v113, v200, s[50:51]
